# hand-written NSA importance-pass tile body: key masks skipped on fully valid tiles, fused DPP rotate-adds, LDS atomics batched (same arithmetic op for op)
# speedup vs baseline: 1.0307x; 1.0010x over previous
; #define LAS __attribute__((address_space(3)))
; template <int DQK> __device__ __forceinline__ void qk_tile(LAS unsigned char* lds, const bf16x8 (&qf)[DQK / 32], f32x4 (&s)[4], int fr, int fq) {
;     constexpr int NKS = DQK / 32;
; #pragma unroll
;     for (int ss = 0; ss < 4; ++ss) {
;         s[ss] = (f32x4){0.f, 0.f, 0.f, 0.f};
; #pragma unroll
;         for (int ks = 0; ks < NKS; ++ks) {
;             const bf16x8 kf = *(const LAS bf16x8*)(lds + k_off<DQK>(16 * ss + fr, 4 * ks + fq));
;             s[ss] = __builtin_amdgcn_mfma_f32_16x16x32_bf16(kf, qf[ks], s[ss], 0, 0, 0);
;         }
;     }
; }
; __device__ __forceinline__ void nsa_item(LAS unsigned char* lds, const NsaPtrs& P, int b, int g, int qb, int tid) {
;     ...
;         if (16 * (64 * t) + 31 > wave_tmax) continue;
; #pragma unroll
;         for (int i = 0; i < 2; ++i) {
;             f32x4 s[4];
;             qk_tile<64>(lds, qf[i], s, fr_i, fq_i);
; #pragma unroll
;             for (int ss = 0; ss < 4; ++ss) {
;                 float a = 0.f, b3 = 0.f;
; #pragma unroll
;                 for (int e = 0; e < 4; ++e) { const int n = 64 * t + 16 * ss + 4 * fq_i + e; const float p = (16 * n + 31 <= tpos[i]) ? __builtin_amdgcn_exp2f(s[ss][e] - mf[i]) * li[i] : 0.f; a += p; if (e == 3) b3 = p; }
;                 a += __shfl_xor(a, 4); a += __shfl_xor(a, 8); b3 += __shfl_xor(b3, 4); b3 += __shfl_xor(b3, 8);
;                 if (fr_i < 4) { const int jp = 16 * t + 4 * ss + fq_i;
;                     __hip_atomic_fetch_add(imp + tok[i] * ISTR + jp, a, __ATOMIC_RELAXED, __HIP_MEMORY_SCOPE_WORKGROUP);
;                     __hip_atomic_fetch_add(imp + tok[i] * ISTR + jp + 1, b3, __ATOMIC_RELAXED, __HIP_MEMORY_SCOPE_WORKGROUP); }
;             }
.LBB0_1022:
	s_add_i32 s6, s10, 31
	v_cmp_le_u32_e64 s[6:7], s6, v136
	s_and_saveexec_b64 s[8:9], s[6:7]
	s_cbranch_execz .LBB0_1019
	ds_read_b128 v[44:47], v71
	ds_read_b128 v[48:51], v72
	ds_read_b128 v[40:43], v71 offset:2048
	ds_read_b128 v[32:35], v72 offset:2048
	ds_read_b128 v[36:39], v71 offset:4096
	ds_read_b128 v[28:31], v72 offset:4096
	ds_read_b128 v[24:27], v71 offset:6144
	ds_read_b128 v[20:23], v72 offset:6144
	v_min_u32_e32 v57, v114, v116
	v_add_u32_e32 v56, s10, v65
	s_waitcnt lgkmcnt(6)
	v_mfma_f32_16x16x32_bf16 v[220:223], v[44:47], v[0:3], 0
	v_mfma_f32_16x16x32_bf16 v[220:223], v[48:51], v[4:7], v[220:223]
	s_waitcnt lgkmcnt(4)
	v_mfma_f32_16x16x32_bf16 v[224:227], v[40:43], v[0:3], 0
	v_mfma_f32_16x16x32_bf16 v[224:227], v[32:35], v[4:7], v[224:227]
	s_waitcnt lgkmcnt(2)
	v_mfma_f32_16x16x32_bf16 v[228:231], v[36:39], v[0:3], 0
	v_mfma_f32_16x16x32_bf16 v[228:231], v[28:31], v[4:7], v[228:231]
	s_waitcnt lgkmcnt(0)
	v_mfma_f32_16x16x32_bf16 v[232:235], v[24:27], v[0:3], 0
	v_mfma_f32_16x16x32_bf16 v[232:235], v[20:23], v[4:7], v[232:235]
	v_mfma_f32_16x16x32_bf16 v[236:239], v[44:47], v[8:11], 0
	v_mfma_f32_16x16x32_bf16 v[236:239], v[48:51], v[12:15], v[236:239]
	v_mfma_f32_16x16x32_bf16 v[240:243], v[40:43], v[8:11], 0
	v_mfma_f32_16x16x32_bf16 v[240:243], v[32:35], v[12:15], v[240:243]
	v_mfma_f32_16x16x32_bf16 v[244:247], v[36:39], v[8:11], 0
	v_mfma_f32_16x16x32_bf16 v[244:247], v[28:31], v[12:15], v[244:247]
	v_mfma_f32_16x16x32_bf16 v[204:207], v[24:27], v[8:11], 0
	v_mfma_f32_16x16x32_bf16 v[204:207], v[20:23], v[12:15], v[204:207]
	s_add_i32 s6, s10, 0x40f
	v_cmp_gt_u32_e64 s[60:61], s6, v57
	s_nop 1
	s_cmp_lg_u64 s[60:61], 0
	s_cbranch_scc1 .Limp_part
	v_sub_f32_e32 v220, v220, v111
	v_sub_f32_e32 v221, v221, v111
	v_sub_f32_e32 v222, v222, v111
	v_sub_f32_e32 v223, v223, v111
	v_exp_f32_e32 v220, v220
	v_exp_f32_e32 v221, v221
	v_exp_f32_e32 v222, v222
	v_exp_f32_e32 v223, v223
	v_fma_f32 v220, v64, v220, 0
	v_mul_f32_e32 v221, v64, v221
	v_mul_f32_e32 v222, v64, v222
	v_mul_f32_e32 v223, v64, v223
	v_add_f32_e32 v220, v221, v220
	v_add_f32_e32 v220, v222, v220
	v_add_f32_e32 v220, v223, v220
	s_nop 0
	v_add_f32_dpp v223, v223, v223 row_ror:12 row_mask:0xf bank_mask:0xf
	v_add_f32_dpp v220, v220, v220 row_ror:12 row_mask:0xf bank_mask:0xf
	s_nop 0
	v_add_f32_dpp v223, v223, v223 row_ror:8 row_mask:0xf bank_mask:0xf
	v_add_f32_dpp v220, v220, v220 row_ror:8 row_mask:0xf bank_mask:0xf
	v_sub_f32_e32 v224, v224, v111
	v_sub_f32_e32 v225, v225, v111
	v_sub_f32_e32 v226, v226, v111
	v_sub_f32_e32 v227, v227, v111
	v_exp_f32_e32 v224, v224
	v_exp_f32_e32 v225, v225
	v_exp_f32_e32 v226, v226
	v_exp_f32_e32 v227, v227
	v_fma_f32 v224, v64, v224, 0
	v_mul_f32_e32 v225, v64, v225
	v_mul_f32_e32 v226, v64, v226
	v_mul_f32_e32 v227, v64, v227
	v_add_f32_e32 v224, v225, v224
	v_add_f32_e32 v224, v226, v224
	v_add_f32_e32 v224, v227, v224
	s_nop 0
	v_add_f32_dpp v227, v227, v227 row_ror:12 row_mask:0xf bank_mask:0xf
	v_add_f32_dpp v224, v224, v224 row_ror:12 row_mask:0xf bank_mask:0xf
	s_nop 0
	v_add_f32_dpp v227, v227, v227 row_ror:8 row_mask:0xf bank_mask:0xf
	v_add_f32_dpp v224, v224, v224 row_ror:8 row_mask:0xf bank_mask:0xf
	v_sub_f32_e32 v228, v228, v111
	v_sub_f32_e32 v229, v229, v111
	v_sub_f32_e32 v230, v230, v111
	v_sub_f32_e32 v231, v231, v111
	v_exp_f32_e32 v228, v228
	v_exp_f32_e32 v229, v229
	v_exp_f32_e32 v230, v230
	v_exp_f32_e32 v231, v231
	v_fma_f32 v228, v64, v228, 0
	v_mul_f32_e32 v229, v64, v229
	v_mul_f32_e32 v230, v64, v230
	v_mul_f32_e32 v231, v64, v231
	v_add_f32_e32 v228, v229, v228
	v_add_f32_e32 v228, v230, v228
	v_add_f32_e32 v228, v231, v228
	s_nop 0
	v_add_f32_dpp v231, v231, v231 row_ror:12 row_mask:0xf bank_mask:0xf
	v_add_f32_dpp v228, v228, v228 row_ror:12 row_mask:0xf bank_mask:0xf
	s_nop 0
	v_add_f32_dpp v231, v231, v231 row_ror:8 row_mask:0xf bank_mask:0xf
	v_add_f32_dpp v228, v228, v228 row_ror:8 row_mask:0xf bank_mask:0xf
	v_sub_f32_e32 v232, v232, v111
	v_sub_f32_e32 v233, v233, v111
	v_sub_f32_e32 v234, v234, v111
	v_sub_f32_e32 v235, v235, v111
	v_exp_f32_e32 v232, v232
	v_exp_f32_e32 v233, v233
	v_exp_f32_e32 v234, v234
	v_exp_f32_e32 v235, v235
	v_fma_f32 v232, v64, v232, 0
	v_mul_f32_e32 v233, v64, v233
	v_mul_f32_e32 v234, v64, v234
	v_mul_f32_e32 v235, v64, v235
	v_add_f32_e32 v232, v233, v232
	v_add_f32_e32 v232, v234, v232
	v_add_f32_e32 v232, v235, v232
	s_nop 0
	v_add_f32_dpp v235, v235, v235 row_ror:12 row_mask:0xf bank_mask:0xf
	v_add_f32_dpp v232, v232, v232 row_ror:12 row_mask:0xf bank_mask:0xf
	s_nop 0
	v_add_f32_dpp v235, v235, v235 row_ror:8 row_mask:0xf bank_mask:0xf
	v_add_f32_dpp v232, v232, v232 row_ror:8 row_mask:0xf bank_mask:0xf
	v_sub_f32_e32 v236, v236, v110
	v_sub_f32_e32 v237, v237, v110
	v_sub_f32_e32 v238, v238, v110
	v_sub_f32_e32 v239, v239, v110
	v_exp_f32_e32 v236, v236
	v_exp_f32_e32 v237, v237
	v_exp_f32_e32 v238, v238
	v_exp_f32_e32 v239, v239
	v_fma_f32 v236, v66, v236, 0
	v_mul_f32_e32 v237, v66, v237
	v_mul_f32_e32 v238, v66, v238
	v_mul_f32_e32 v239, v66, v239
	v_add_f32_e32 v236, v237, v236
	v_add_f32_e32 v236, v238, v236
	v_add_f32_e32 v236, v239, v236
	s_nop 0
	v_add_f32_dpp v239, v239, v239 row_ror:12 row_mask:0xf bank_mask:0xf
	v_add_f32_dpp v236, v236, v236 row_ror:12 row_mask:0xf bank_mask:0xf
	s_nop 0
	v_add_f32_dpp v239, v239, v239 row_ror:8 row_mask:0xf bank_mask:0xf
	v_add_f32_dpp v236, v236, v236 row_ror:8 row_mask:0xf bank_mask:0xf
	v_sub_f32_e32 v240, v240, v110
	v_sub_f32_e32 v241, v241, v110
	v_sub_f32_e32 v242, v242, v110
	v_sub_f32_e32 v243, v243, v110
	v_exp_f32_e32 v240, v240
	v_exp_f32_e32 v241, v241
; __device__ __forceinline__ void nsa_item(LAS unsigned char* lds, const NsaPtrs& P, int b, int g, int qb, int tid) {
;     ...
;             for (int ss = 0; ss < 4; ++ss) {
;                 float a = 0.f, b3 = 0.f;
; #pragma unroll
;                 for (int e = 0; e < 4; ++e) { const int n = 64 * t + 16 * ss + 4 * fq_i + e; const float p = (16 * n + 31 <= tpos[i]) ? __builtin_amdgcn_exp2f(s[ss][e] - mf[i]) * li[i] : 0.f; a += p; if (e == 3) b3 = p; }
;                 a += __shfl_xor(a, 4); a += __shfl_xor(a, 8); b3 += __shfl_xor(b3, 4); b3 += __shfl_xor(b3, 8);
;                 if (fr_i < 4) { const int jp = 16 * t + 4 * ss + fq_i;
;                     __hip_atomic_fetch_add(imp + tok[i] * ISTR + jp, a, __ATOMIC_RELAXED, __HIP_MEMORY_SCOPE_WORKGROUP);
;                     __hip_atomic_fetch_add(imp + tok[i] * ISTR + jp + 1, b3, __ATOMIC_RELAXED, __HIP_MEMORY_SCOPE_WORKGROUP); }
	v_exp_f32_e32 v242, v242
	v_exp_f32_e32 v243, v243
	v_fma_f32 v240, v66, v240, 0
	v_mul_f32_e32 v241, v66, v241
	v_mul_f32_e32 v242, v66, v242
	v_mul_f32_e32 v243, v66, v243
	v_add_f32_e32 v240, v241, v240
	v_add_f32_e32 v240, v242, v240
	v_add_f32_e32 v240, v243, v240
	s_nop 0
	v_add_f32_dpp v243, v243, v243 row_ror:12 row_mask:0xf bank_mask:0xf
	v_add_f32_dpp v240, v240, v240 row_ror:12 row_mask:0xf bank_mask:0xf
	s_nop 0
	v_add_f32_dpp v243, v243, v243 row_ror:8 row_mask:0xf bank_mask:0xf
	v_add_f32_dpp v240, v240, v240 row_ror:8 row_mask:0xf bank_mask:0xf
	v_sub_f32_e32 v244, v244, v110
	v_sub_f32_e32 v245, v245, v110
	v_sub_f32_e32 v246, v246, v110
	v_sub_f32_e32 v247, v247, v110
	v_exp_f32_e32 v244, v244
	v_exp_f32_e32 v245, v245
	v_exp_f32_e32 v246, v246
	v_exp_f32_e32 v247, v247
	v_fma_f32 v244, v66, v244, 0
	v_mul_f32_e32 v245, v66, v245
	v_mul_f32_e32 v246, v66, v246
	v_mul_f32_e32 v247, v66, v247
	v_add_f32_e32 v244, v245, v244
	v_add_f32_e32 v244, v246, v244
	v_add_f32_e32 v244, v247, v244
	s_nop 0
	v_add_f32_dpp v247, v247, v247 row_ror:12 row_mask:0xf bank_mask:0xf
	v_add_f32_dpp v244, v244, v244 row_ror:12 row_mask:0xf bank_mask:0xf
	s_nop 0
	v_add_f32_dpp v247, v247, v247 row_ror:8 row_mask:0xf bank_mask:0xf
	v_add_f32_dpp v244, v244, v244 row_ror:8 row_mask:0xf bank_mask:0xf
	v_sub_f32_e32 v204, v204, v110
	v_sub_f32_e32 v205, v205, v110
	v_sub_f32_e32 v206, v206, v110
	v_sub_f32_e32 v207, v207, v110
	v_exp_f32_e32 v204, v204
	v_exp_f32_e32 v205, v205
	v_exp_f32_e32 v206, v206
	v_exp_f32_e32 v207, v207
	v_fma_f32 v204, v66, v204, 0
	v_mul_f32_e32 v205, v66, v205
	v_mul_f32_e32 v206, v66, v206
	v_mul_f32_e32 v207, v66, v207
	v_add_f32_e32 v204, v205, v204
	v_add_f32_e32 v204, v206, v204
	v_add_f32_e32 v204, v207, v204
	s_nop 0
	v_add_f32_dpp v207, v207, v207 row_ror:12 row_mask:0xf bank_mask:0xf
	v_add_f32_dpp v204, v204, v204 row_ror:12 row_mask:0xf bank_mask:0xf
	s_nop 0
	v_add_f32_dpp v207, v207, v207 row_ror:8 row_mask:0xf bank_mask:0xf
	v_add_f32_dpp v204, v204, v204 row_ror:8 row_mask:0xf bank_mask:0xf
.Limp_store:
	s_and_b64 exec, exec, vcc
	s_cbranch_execz .LBB0_1019
	ds_add_f32 v67, v220
	ds_add_f32 v67, v223 offset:4
	ds_add_f32 v67, v224 offset:16
	ds_add_f32 v67, v227 offset:20
	ds_add_f32 v67, v228 offset:32
	ds_add_f32 v67, v231 offset:36
	ds_add_f32 v67, v232 offset:48
	ds_add_f32 v67, v235 offset:52
	ds_add_f32 v67, v236 offset:2112
	ds_add_f32 v67, v239 offset:2116
	ds_add_f32 v67, v240 offset:2128
	ds_add_f32 v67, v243 offset:2132
	ds_add_f32 v67, v244 offset:2144
	ds_add_f32 v67, v247 offset:2148
	ds_add_f32 v67, v204 offset:2160
	ds_add_f32 v67, v207 offset:2164
	s_branch .LBB0_1019
.Limp_part:
	v_sub_f32_e32 v220, v220, v111
	v_sub_f32_e32 v221, v221, v111
	v_sub_f32_e32 v222, v222, v111
	v_sub_f32_e32 v223, v223, v111
	v_exp_f32_e32 v220, v220
	v_exp_f32_e32 v221, v221
	v_exp_f32_e32 v222, v222
	v_exp_f32_e32 v223, v223
	v_fma_f32 v220, v64, v220, 0
	v_mul_f32_e32 v221, v64, v221
	v_mul_f32_e32 v222, v64, v222
	v_mul_f32_e32 v223, v64, v223
	v_add_u32_e32 v52, 31, v56
	v_add_u32_e32 v53, 47, v56
	v_add_u32_e32 v54, 63, v56
	v_add_u32_e32 v55, 79, v56
	v_cmp_le_u32_e64 s[12:13], v52, v114
	v_cmp_le_u32_e64 s[14:15], v53, v114
	v_cmp_le_u32_e64 s[20:21], v54, v114
	v_cndmask_b32_e64 v220, 0, v220, s[12:13]
	v_cmp_le_u32_e64 s[12:13], v55, v114
	v_cndmask_b32_e64 v221, 0, v221, s[14:15]
	v_cndmask_b32_e64 v222, 0, v222, s[20:21]
	s_nop 0
	v_cndmask_b32_e64 v223, 0, v223, s[12:13]
	v_add_f32_e32 v220, v221, v220
	v_add_f32_e32 v220, v222, v220
	v_add_f32_e32 v220, v223, v220
	s_nop 0
	v_add_f32_dpp v223, v223, v223 row_ror:12 row_mask:0xf bank_mask:0xf
	v_add_f32_dpp v220, v220, v220 row_ror:12 row_mask:0xf bank_mask:0xf
	s_nop 0
	v_add_f32_dpp v223, v223, v223 row_ror:8 row_mask:0xf bank_mask:0xf
	v_add_f32_dpp v220, v220, v220 row_ror:8 row_mask:0xf bank_mask:0xf
	v_sub_f32_e32 v224, v224, v111
	v_sub_f32_e32 v225, v225, v111
	v_sub_f32_e32 v226, v226, v111
	v_sub_f32_e32 v227, v227, v111
	v_exp_f32_e32 v224, v224
	v_exp_f32_e32 v225, v225
	v_exp_f32_e32 v226, v226
	v_exp_f32_e32 v227, v227
	v_fma_f32 v224, v64, v224, 0
	v_mul_f32_e32 v225, v64, v225
	v_mul_f32_e32 v226, v64, v226
	v_mul_f32_e32 v227, v64, v227
	v_add_u32_e32 v52, 287, v56
	v_add_u32_e32 v53, 303, v56
	v_add_u32_e32 v54, 319, v56
	v_add_u32_e32 v55, 335, v56
	v_cmp_le_u32_e64 s[12:13], v52, v114
	v_cmp_le_u32_e64 s[14:15], v53, v114
	v_cmp_le_u32_e64 s[20:21], v54, v114
	v_cndmask_b32_e64 v224, 0, v224, s[12:13]
	v_cmp_le_u32_e64 s[12:13], v55, v114
	v_cndmask_b32_e64 v225, 0, v225, s[14:15]
	v_cndmask_b32_e64 v226, 0, v226, s[20:21]
	s_nop 0
	v_cndmask_b32_e64 v227, 0, v227, s[12:13]
	v_add_f32_e32 v224, v225, v224
	v_add_f32_e32 v224, v226, v224
	v_add_f32_e32 v224, v227, v224
	s_nop 0
	v_add_f32_dpp v227, v227, v227 row_ror:12 row_mask:0xf bank_mask:0xf
	v_add_f32_dpp v224, v224, v224 row_ror:12 row_mask:0xf bank_mask:0xf
	s_nop 0
	v_add_f32_dpp v227, v227, v227 row_ror:8 row_mask:0xf bank_mask:0xf
	v_add_f32_dpp v224, v224, v224 row_ror:8 row_mask:0xf bank_mask:0xf
	v_sub_f32_e32 v228, v228, v111
	v_sub_f32_e32 v229, v229, v111
	v_sub_f32_e32 v230, v230, v111
	v_sub_f32_e32 v231, v231, v111
	v_exp_f32_e32 v228, v228
	v_exp_f32_e32 v229, v229
	v_exp_f32_e32 v230, v230
	v_exp_f32_e32 v231, v231
	v_fma_f32 v228, v64, v228, 0
	v_mul_f32_e32 v229, v64, v229
	v_mul_f32_e32 v230, v64, v230
	v_mul_f32_e32 v231, v64, v231
	v_add_u32_e32 v52, 543, v56
	v_add_u32_e32 v53, 559, v56
	v_add_u32_e32 v54, 575, v56
	v_add_u32_e32 v55, 591, v56
	v_cmp_le_u32_e64 s[12:13], v52, v114
	v_cmp_le_u32_e64 s[14:15], v53, v114
	v_cmp_le_u32_e64 s[20:21], v54, v114
; __device__ __forceinline__ void nsa_item(LAS unsigned char* lds, const NsaPtrs& P, int b, int g, int qb, int tid) {
;     ...
;             for (int ss = 0; ss < 4; ++ss) {
;                 float a = 0.f, b3 = 0.f;
; #pragma unroll
;                 for (int e = 0; e < 4; ++e) { const int n = 64 * t + 16 * ss + 4 * fq_i + e; const float p = (16 * n + 31 <= tpos[i]) ? __builtin_amdgcn_exp2f(s[ss][e] - mf[i]) * li[i] : 0.f; a += p; if (e == 3) b3 = p; }
;                 a += __shfl_xor(a, 4); a += __shfl_xor(a, 8); b3 += __shfl_xor(b3, 4); b3 += __shfl_xor(b3, 8);
;                 if (fr_i < 4) { const int jp = 16 * t + 4 * ss + fq_i;
;                     __hip_atomic_fetch_add(imp + tok[i] * ISTR + jp, a, __ATOMIC_RELAXED, __HIP_MEMORY_SCOPE_WORKGROUP);
;                     __hip_atomic_fetch_add(imp + tok[i] * ISTR + jp + 1, b3, __ATOMIC_RELAXED, __HIP_MEMORY_SCOPE_WORKGROUP); }
	v_cndmask_b32_e64 v228, 0, v228, s[12:13]
	v_cmp_le_u32_e64 s[12:13], v55, v114
	v_cndmask_b32_e64 v229, 0, v229, s[14:15]
	v_cndmask_b32_e64 v230, 0, v230, s[20:21]
	s_nop 0
	v_cndmask_b32_e64 v231, 0, v231, s[12:13]
	v_add_f32_e32 v228, v229, v228
	v_add_f32_e32 v228, v230, v228
	v_add_f32_e32 v228, v231, v228
	s_nop 0
	v_add_f32_dpp v231, v231, v231 row_ror:12 row_mask:0xf bank_mask:0xf
	v_add_f32_dpp v228, v228, v228 row_ror:12 row_mask:0xf bank_mask:0xf
	s_nop 0
	v_add_f32_dpp v231, v231, v231 row_ror:8 row_mask:0xf bank_mask:0xf
	v_add_f32_dpp v228, v228, v228 row_ror:8 row_mask:0xf bank_mask:0xf
	v_sub_f32_e32 v232, v232, v111
	v_sub_f32_e32 v233, v233, v111
	v_sub_f32_e32 v234, v234, v111
	v_sub_f32_e32 v235, v235, v111
	v_exp_f32_e32 v232, v232
	v_exp_f32_e32 v233, v233
	v_exp_f32_e32 v234, v234
	v_exp_f32_e32 v235, v235
	v_fma_f32 v232, v64, v232, 0
	v_mul_f32_e32 v233, v64, v233
	v_mul_f32_e32 v234, v64, v234
	v_mul_f32_e32 v235, v64, v235
	v_add_u32_e32 v52, 799, v56
	v_add_u32_e32 v53, 815, v56
	v_add_u32_e32 v54, 831, v56
	v_add_u32_e32 v55, 847, v56
	v_cmp_le_u32_e64 s[12:13], v52, v114
	v_cmp_le_u32_e64 s[14:15], v53, v114
	v_cmp_le_u32_e64 s[20:21], v54, v114
	v_cndmask_b32_e64 v232, 0, v232, s[12:13]
	v_cmp_le_u32_e64 s[12:13], v55, v114
	v_cndmask_b32_e64 v233, 0, v233, s[14:15]
	v_cndmask_b32_e64 v234, 0, v234, s[20:21]
	s_nop 0
	v_cndmask_b32_e64 v235, 0, v235, s[12:13]
	v_add_f32_e32 v232, v233, v232
	v_add_f32_e32 v232, v234, v232
	v_add_f32_e32 v232, v235, v232
	s_nop 0
	v_add_f32_dpp v235, v235, v235 row_ror:12 row_mask:0xf bank_mask:0xf
	v_add_f32_dpp v232, v232, v232 row_ror:12 row_mask:0xf bank_mask:0xf
	s_nop 0
	v_add_f32_dpp v235, v235, v235 row_ror:8 row_mask:0xf bank_mask:0xf
	v_add_f32_dpp v232, v232, v232 row_ror:8 row_mask:0xf bank_mask:0xf
	v_sub_f32_e32 v236, v236, v110
	v_sub_f32_e32 v237, v237, v110
	v_sub_f32_e32 v238, v238, v110
	v_sub_f32_e32 v239, v239, v110
	v_exp_f32_e32 v236, v236
	v_exp_f32_e32 v237, v237
	v_exp_f32_e32 v238, v238
	v_exp_f32_e32 v239, v239
	v_fma_f32 v236, v66, v236, 0
	v_mul_f32_e32 v237, v66, v237
	v_mul_f32_e32 v238, v66, v238
	v_mul_f32_e32 v239, v66, v239
	v_add_u32_e32 v52, 31, v56
	v_add_u32_e32 v53, 47, v56
	v_add_u32_e32 v54, 63, v56
	v_add_u32_e32 v55, 79, v56
	v_cmp_le_u32_e64 s[12:13], v52, v116
	v_cmp_le_u32_e64 s[14:15], v53, v116
	v_cmp_le_u32_e64 s[20:21], v54, v116
	v_cndmask_b32_e64 v236, 0, v236, s[12:13]
	v_cmp_le_u32_e64 s[12:13], v55, v116
	v_cndmask_b32_e64 v237, 0, v237, s[14:15]
	v_cndmask_b32_e64 v238, 0, v238, s[20:21]
	s_nop 0
	v_cndmask_b32_e64 v239, 0, v239, s[12:13]
	v_add_f32_e32 v236, v237, v236
	v_add_f32_e32 v236, v238, v236
	v_add_f32_e32 v236, v239, v236
	s_nop 0
	v_add_f32_dpp v239, v239, v239 row_ror:12 row_mask:0xf bank_mask:0xf
	v_add_f32_dpp v236, v236, v236 row_ror:12 row_mask:0xf bank_mask:0xf
	s_nop 0
	v_add_f32_dpp v239, v239, v239 row_ror:8 row_mask:0xf bank_mask:0xf
	v_add_f32_dpp v236, v236, v236 row_ror:8 row_mask:0xf bank_mask:0xf
	v_sub_f32_e32 v240, v240, v110
	v_sub_f32_e32 v241, v241, v110
	v_sub_f32_e32 v242, v242, v110
	v_sub_f32_e32 v243, v243, v110
	v_exp_f32_e32 v240, v240
	v_exp_f32_e32 v241, v241
	v_exp_f32_e32 v242, v242
	v_exp_f32_e32 v243, v243
	v_fma_f32 v240, v66, v240, 0
	v_mul_f32_e32 v241, v66, v241
	v_mul_f32_e32 v242, v66, v242
	v_mul_f32_e32 v243, v66, v243
	v_add_u32_e32 v52, 287, v56
	v_add_u32_e32 v53, 303, v56
	v_add_u32_e32 v54, 319, v56
	v_add_u32_e32 v55, 335, v56
	v_cmp_le_u32_e64 s[12:13], v52, v116
	v_cmp_le_u32_e64 s[14:15], v53, v116
	v_cmp_le_u32_e64 s[20:21], v54, v116
	v_cndmask_b32_e64 v240, 0, v240, s[12:13]
	v_cmp_le_u32_e64 s[12:13], v55, v116
	v_cndmask_b32_e64 v241, 0, v241, s[14:15]
	v_cndmask_b32_e64 v242, 0, v242, s[20:21]
	s_nop 0
	v_cndmask_b32_e64 v243, 0, v243, s[12:13]
	v_add_f32_e32 v240, v241, v240
	v_add_f32_e32 v240, v242, v240
	v_add_f32_e32 v240, v243, v240
	s_nop 0
	v_add_f32_dpp v243, v243, v243 row_ror:12 row_mask:0xf bank_mask:0xf
	v_add_f32_dpp v240, v240, v240 row_ror:12 row_mask:0xf bank_mask:0xf
	s_nop 0
	v_add_f32_dpp v243, v243, v243 row_ror:8 row_mask:0xf bank_mask:0xf
	v_add_f32_dpp v240, v240, v240 row_ror:8 row_mask:0xf bank_mask:0xf
	v_sub_f32_e32 v244, v244, v110
	v_sub_f32_e32 v245, v245, v110
	v_sub_f32_e32 v246, v246, v110
	v_sub_f32_e32 v247, v247, v110
	v_exp_f32_e32 v244, v244
	v_exp_f32_e32 v245, v245
	v_exp_f32_e32 v246, v246
	v_exp_f32_e32 v247, v247
	v_fma_f32 v244, v66, v244, 0
	v_mul_f32_e32 v245, v66, v245
	v_mul_f32_e32 v246, v66, v246
	v_mul_f32_e32 v247, v66, v247
	v_add_u32_e32 v52, 543, v56
	v_add_u32_e32 v53, 559, v56
	v_add_u32_e32 v54, 575, v56
	v_add_u32_e32 v55, 591, v56
	v_cmp_le_u32_e64 s[12:13], v52, v116
	v_cmp_le_u32_e64 s[14:15], v53, v116
	v_cmp_le_u32_e64 s[20:21], v54, v116
	v_cndmask_b32_e64 v244, 0, v244, s[12:13]
	v_cmp_le_u32_e64 s[12:13], v55, v116
	v_cndmask_b32_e64 v245, 0, v245, s[14:15]
	v_cndmask_b32_e64 v246, 0, v246, s[20:21]
	s_nop 0
	v_cndmask_b32_e64 v247, 0, v247, s[12:13]
	v_add_f32_e32 v244, v245, v244
	v_add_f32_e32 v244, v246, v244
	v_add_f32_e32 v244, v247, v244
	s_nop 0
	v_add_f32_dpp v247, v247, v247 row_ror:12 row_mask:0xf bank_mask:0xf
	v_add_f32_dpp v244, v244, v244 row_ror:12 row_mask:0xf bank_mask:0xf
	s_nop 0
	v_add_f32_dpp v247, v247, v247 row_ror:8 row_mask:0xf bank_mask:0xf
	v_add_f32_dpp v244, v244, v244 row_ror:8 row_mask:0xf bank_mask:0xf
	v_sub_f32_e32 v204, v204, v110
	v_sub_f32_e32 v205, v205, v110
	v_sub_f32_e32 v206, v206, v110
	v_sub_f32_e32 v207, v207, v110
	v_exp_f32_e32 v204, v204
	v_exp_f32_e32 v205, v205
	v_exp_f32_e32 v206, v206
	v_exp_f32_e32 v207, v207
	v_fma_f32 v204, v66, v204, 0
	v_mul_f32_e32 v205, v66, v205
	v_mul_f32_e32 v206, v66, v206
	v_mul_f32_e32 v207, v66, v207
	v_add_u32_e32 v52, 799, v56
	v_add_u32_e32 v53, 815, v56
	v_add_u32_e32 v54, 831, v56
	v_add_u32_e32 v55, 847, v56
	v_cmp_le_u32_e64 s[12:13], v52, v116
	v_cmp_le_u32_e64 s[14:15], v53, v116
	v_cmp_le_u32_e64 s[20:21], v54, v116
	v_cndmask_b32_e64 v204, 0, v204, s[12:13]
	v_cmp_le_u32_e64 s[12:13], v55, v116
	v_cndmask_b32_e64 v205, 0, v205, s[14:15]
	v_cndmask_b32_e64 v206, 0, v206, s[20:21]
	s_nop 0
	v_cndmask_b32_e64 v207, 0, v207, s[12:13]
	v_add_f32_e32 v204, v205, v204
	v_add_f32_e32 v204, v206, v204
	v_add_f32_e32 v204, v207, v204
	s_nop 0
	v_add_f32_dpp v207, v207, v207 row_ror:12 row_mask:0xf bank_mask:0xf
	v_add_f32_dpp v204, v204, v204 row_ror:12 row_mask:0xf bank_mask:0xf
	s_nop 0
	v_add_f32_dpp v207, v207, v207 row_ror:8 row_mask:0xf bank_mask:0xf
	v_add_f32_dpp v204, v204, v204 row_ror:8 row_mask:0xf bank_mask:0xf
	s_branch .Limp_store
